# attention 96-dim main loop: QK as s0 chain then s1 chain with the second-half K fragment reads hidden behind MFMAs, s0 exps in s1 MFMA gaps, exps in place
# speedup vs baseline: 1.0640x; 1.0016x over previous
.LBB0_363:
	s_or_b64 exec, exec, s[8:9]
	s_waitcnt lgkmcnt(7)
	v_mfma_f32_32x32x16_bf16 v[64:79], v[60:63], v[80:83], v[32:47]
	s_mul_i32 s8, s42, 0x3400
	v_add_u32_e32 v124, s8, v208
	ds_read_b128 v[108:111], v124 offset:96
	ds_read_b128 v[116:119], v124 offset:128
	ds_read_b128 v[120:123], v124 offset:160
	s_waitcnt lgkmcnt(7)
	v_mfma_f32_32x32x16_bf16 v[64:79], v[156:159], v[84:87], v[64:79]
	v_mfma_f32_32x32x16_bf16 v[64:79], v[152:155], v[88:91], v[64:79]
	s_waitcnt lgkmcnt(2)
	v_mfma_f32_32x32x16_bf16 v[64:79], v[108:111], v[92:95], v[64:79]
	s_waitcnt lgkmcnt(1)
	v_mfma_f32_32x32x16_bf16 v[64:79], v[116:119], v[96:99], v[64:79]
	s_waitcnt lgkmcnt(0)
	v_mfma_f32_32x32x16_bf16 v[64:79], v[120:123], v[100:103], v[64:79]
	ds_read_b128 v[108:111], v124 offset:6752
	ds_read_b128 v[116:119], v124 offset:6784
	ds_read_b128 v[120:123], v124 offset:6816
	v_mfma_f32_32x32x16_bf16 v[48:63], v[164:167], v[80:83], v[32:47]
	v_mfma_f32_32x32x16_bf16 v[48:63], v[160:163], v[84:87], v[48:63]
	v_mfma_f32_32x32x16_bf16 v[48:63], v[148:151], v[88:91], v[48:63]
	s_waitcnt lgkmcnt(2)
	v_mfma_f32_32x32x16_bf16 v[48:63], v[108:111], v[92:95], v[48:63]
	global_load_dwordx4 v[108:111], v[196:197], off
	s_nop 2
	v_exp_f32_e32 v64, v64
	v_exp_f32_e32 v65, v65
	v_exp_f32_e32 v66, v66
	v_exp_f32_e32 v67, v67
	v_exp_f32_e32 v68, v68
	s_waitcnt lgkmcnt(1)
	v_mfma_f32_32x32x16_bf16 v[48:63], v[116:119], v[96:99], v[48:63]
	v_exp_f32_e32 v69, v69
	v_exp_f32_e32 v70, v70
	v_exp_f32_e32 v71, v71
	v_exp_f32_e32 v72, v72
	v_exp_f32_e32 v73, v73
	s_waitcnt lgkmcnt(0)
	v_mfma_f32_32x32x16_bf16 v[48:63], v[120:123], v[100:103], v[48:63]
	v_exp_f32_e32 v74, v74
	v_exp_f32_e32 v75, v75
	v_exp_f32_e32 v76, v76
	v_exp_f32_e32 v77, v77
	v_exp_f32_e32 v78, v78
	v_exp_f32_e32 v79, v79
	s_setprio 0
	s_and_b32 s72, 1, s33
	s_cselect_b32 s8, 0, 0x2400
	v_add_u32_e32 v116, s8, v209
	ds_read_b128 v[140:143], v116 offset:39936
	ds_read_b128 v[128:131], v116 offset:39968
	ds_read_b128 v[144:147], v116 offset:44544
	ds_read_b128 v[132:135], v116 offset:44576
	ds_read_b128 v[124:127], v116 offset:40000
	ds_read_b128 v[120:123], v116 offset:40032
	ds_read_b128 v[136:139], v116 offset:44608
	ds_read_b128 v[116:119], v116 offset:44640
.LBB0_365:
	v_exp_f32_e32 v48, v48
	v_exp_f32_e32 v49, v49
	v_exp_f32_e32 v50, v50
	v_exp_f32_e32 v51, v51
	v_exp_f32_e32 v52, v52
	v_exp_f32_e32 v53, v53
	v_exp_f32_e32 v54, v54
	v_exp_f32_e32 v55, v55
	s_cmp_eq_u32 s98, 0
	s_cbranch_scc1 .Lstg_x_11
	s_waitcnt lgkmcnt(0)
	s_barrier
.Lstg_x_11:
	v_exp_f32_e32 v56, v56
	v_exp_f32_e32 v57, v57
	v_exp_f32_e32 v58, v58
	v_exp_f32_e32 v59, v59
	v_exp_f32_e32 v219, v60
	v_exp_f32_e32 v220, v61
	v_exp_f32_e32 v221, v62
	v_exp_f32_e32 v222, v63
	v_cvt_pk_bf16_f32 v224, v64, v65
	v_cvt_pk_bf16_f32 v225, v66, v67
	v_cvt_pk_bf16_f32 v226, v68, v69
	v_cvt_pk_bf16_f32 v227, v70, v71
	v_cvt_pk_bf16_f32 v228, v72, v73
	v_cvt_pk_bf16_f32 v229, v74, v75
	v_cvt_pk_bf16_f32 v230, v76, v77
	v_cvt_pk_bf16_f32 v231, v78, v79
	v_cvt_pk_bf16_f32 v232, v48, v49
	v_cvt_pk_bf16_f32 v233, v50, v51
	v_cvt_pk_bf16_f32 v234, v52, v53
	v_cvt_pk_bf16_f32 v235, v54, v55
	v_cvt_pk_bf16_f32 v236, v56, v57
	v_cvt_pk_bf16_f32 v237, v58, v59
	v_cvt_pk_bf16_f32 v238, v219, v220
	v_cvt_pk_bf16_f32 v239, v221, v222
	s_setprio 1
	s_cmp_lg_u32 s98, 0
	s_cbranch_scc1 .Lstg_y_12
	s_waitcnt lgkmcnt(0)
	s_barrier
.Lstg_y_12:
	s_mul_i32 s8, s45, 0x3400
	v_add_u32_e32 v189, s8, v208
	ds_read_b128 v[60:63], v189
	ds_read_b128 v[156:159], v189 offset:32
	ds_read_b128 v[164:167], v189 offset:6656
	ds_read_b128 v[152:155], v189 offset:64
	ds_read_b128 v[160:163], v189 offset:6688
	ds_read_b128 v[148:151], v189 offset:6720
	s_waitcnt lgkmcnt(13)
	v_mfma_f32_32x32x16_bf16 v[16:31], v[140:143], v[224:227], v[16:31]
	v_add_f32_e32 v64, v64, v48
	v_add_f32_e32 v65, v65, v49
	v_add_f32_e32 v66, v66, v50
	v_add_f32_e32 v67, v67, v51
	s_mul_i32 s44, s43, 0x3400
	s_add_i32 s18, s44, 0
	s_waitcnt lgkmcnt(11)
	v_mfma_f32_32x32x16_bf16 v[0:15], v[144:147], v[224:227], v[0:15]
	v_add_f32_e32 v68, v68, v52
	v_add_f32_e32 v69, v69, v53
	v_add_f32_e32 v70, v70, v54
	v_add_f32_e32 v71, v71, v55
	v_mfma_f32_32x32x16_bf16 v[16:31], v[128:131], v[228:231], v[16:31]
	v_add_f32_e32 v72, v72, v56
	v_add_f32_e32 v73, v73, v57
	v_add_f32_e32 v74, v74, v58
	v_add_f32_e32 v75, v75, v59
	s_waitcnt lgkmcnt(10)
	v_mfma_f32_32x32x16_bf16 v[0:15], v[132:135], v[228:231], v[0:15]
	v_add_f32_e32 v76, v76, v219
	v_add_f32_e32 v77, v77, v220
	v_add_f32_e32 v78, v78, v221
	v_add_f32_e32 v79, v79, v222
	s_waitcnt lgkmcnt(9)
	v_mfma_f32_32x32x16_bf16 v[16:31], v[124:127], v[232:235], v[16:31]
	v_add_f32_e32 v64, v64, v65
	v_add_f32_e32 v66, v66, v67
	v_add_f32_e32 v68, v68, v69
	v_add_f32_e32 v70, v70, v71
	s_waitcnt lgkmcnt(7)
	v_mfma_f32_32x32x16_bf16 v[0:15], v[136:139], v[232:235], v[0:15]
	v_add_f32_e32 v72, v72, v73
	v_add_f32_e32 v74, v74, v75
	v_add_f32_e32 v76, v76, v77
	v_add_f32_e32 v78, v78, v79
	v_mfma_f32_32x32x16_bf16 v[16:31], v[120:123], v[236:239], v[16:31]
	v_add_f32_e32 v64, v64, v66
	v_add_f32_e32 v68, v68, v70
	v_add_f32_e32 v72, v72, v74
	v_add_f32_e32 v76, v76, v78
	v_add_u32_e32 v120, s18, v207
	s_waitcnt vmcnt(1)
	ds_write_b128 v120, v[112:115]
	s_waitcnt lgkmcnt(7)
	v_mfma_f32_32x32x16_bf16 v[0:15], v[116:119], v[236:239], v[0:15]
	v_add_f32_e32 v64, v64, v68
	v_add_f32_e32 v72, v72, v76
	s_and_saveexec_b64 s[8:9], s[4:5]
	v_add_u32_e32 v112, s18, v206
	ds_write_b128 v112, v[104:107]
	s_or_b64 exec, exec, s[8:9]
	v_add_f32_e32 v64, v64, v72
	s_cmp_eq_u32 s72, 1
	s_cselect_b32 s8, 0, 0x2400
	v_add_f32_e32 v190, v190, v64
	v_add_u32_e32 v48, s8, v198
	v_add_u32_e32 v48, 0x9800, v48
	s_waitcnt vmcnt(0)
	ds_write2_b64 v48, v[108:109], v[110:111] offset0:128 offset1:130
	s_add_i32 s33, s33, 1
	v_lshl_add_u64 v[194:195], v[194:195], 0, s[36:37]
	s_cmp_eq_u32 s33, 31
	v_lshl_add_u64 v[196:197], v[196:197], 0, s[22:23]
	s_cbranch_scc1 .LBB0_369
	s_mov_b32 s8, s42
	s_mov_b32 s42, s45
	s_branch .LBB0_361
